# RWKV scan: next chunk staged global-to-LDS by LDS-DMA instead of VGPR + ds_write; scan step schedule with U fmas filling DPP wait slots
# speedup vs baseline: 1.0374x; 1.0167x over previous
.LBB0_262:
	s_and_b64 s[0:1], s[6:7], exec
	s_movk_i32 s0, 0x400
	s_cselect_b32 s5, s0, 0x100
	s_lshl_b32 s0, s4, 10
	s_add_i32 s9, s0, 0x1000
	s_lshl_b32 s11, s4, 8
	s_and_b64 s[0:1], s[6:7], exec
	s_cselect_b32 s0, s9, s11
	s_mov_b32 s9, 0x2aaaaaab
	v_mul_hi_i32 v0, v122, s9
	v_lshrrev_b32_e32 v1, 31, v0
	v_ashrrev_i32_e32 v0, 4, v0
	s_movk_i32 s12, 0x60
	v_add_u32_e32 v0, v0, v1
	v_mul_lo_u32 v1, v0, s12
	s_lshr_b32 s1, s5, 4
	s_waitcnt vmcnt(7)
	v_sub_u32_e32 v42, v122, v1
	s_cmp_eq_u32 s10, 0
	v_ashrrev_i32_e32 v1, 4, v42
	s_mul_i32 s6, s10, 3
	v_xad_u32 v2, v0, -1, s5
	s_cselect_b64 s[36:37], -1, 0
	v_mov_b32_e32 v6, s6
	v_cmp_lt_i32_e32 vcc, 2, v1
	v_cndmask_b32_e64 v0, v2, v0, s[36:37]
	v_add_u32_e32 v32, 0x100, v122
	v_cndmask_b32_e32 v2, 0, v6, vcc
	v_add_u32_e32 v34, v2, v1
	v_lshlrev_b32_e32 v2, 4, v42
	v_and_b32_e32 v128, 0xf0, v2
	v_mul_hi_i32 v2, v32, s9
	v_lshrrev_b32_e32 v3, 31, v2
	v_ashrrev_i32_e32 v2, 4, v2
	v_add_u32_e32 v2, v2, v3
	v_mul_lo_u32 v3, v2, s12
	s_waitcnt vmcnt(6)
	v_sub_u32_e32 v44, v32, v3
	v_ashrrev_i32_e32 v3, 4, v44
	v_xad_u32 v4, v2, -1, s5
	v_cmp_lt_i32_e32 vcc, 2, v3
	v_add_u32_e32 v0, s0, v0
	v_cndmask_b32_e64 v2, v4, v2, s[36:37]
	v_cndmask_b32_e32 v4, 0, v6, vcc
	v_lshl_add_u32 v43, v0, 2, s8
	v_ashrrev_i32_e32 v35, 31, v34
	v_add_u32_e32 v36, v4, v3
	v_add_u32_e32 v2, s0, v2
	v_mad_i64_i32 v[0:1], s[6:7], v43, 9, v[34:35]
	v_lshl_add_u32 v45, v2, 2, s8
	v_ashrrev_i32_e32 v37, 31, v36
	v_lshlrev_b64 v[0:1], 8, v[0:1]
	v_mad_i64_i32 v[2:3], s[6:7], v45, 9, v[36:37]
	v_lshl_add_u64 v[0:1], s[20:21], 0, v[0:1]
	v_lshlrev_b64 v[2:3], 8, v[2:3]
	v_lshlrev_b32_e32 v4, 4, v44
	v_lshl_add_u64 v[0:1], v[0:1], 0, v[128:129]
	v_lshl_add_u64 v[2:3], s[20:21], 0, v[2:3]
	v_and_b32_e32 v128, 0xf0, v4
	v_add_u32_e32 v33, 0x200, v122
	v_lshl_add_u64 v[4:5], v[2:3], 0, v[128:129]
	v_mul_hi_i32 v2, v33, s9
	v_lshrrev_b32_e32 v3, 31, v2
	v_ashrrev_i32_e32 v2, 4, v2
	v_add_u32_e32 v2, v2, v3
	v_mul_lo_u32 v3, v2, s12
	s_waitcnt vmcnt(4)
	v_sub_u32_e32 v54, v33, v3
	v_ashrrev_i32_e32 v3, 4, v54
	v_xad_u32 v7, v2, -1, s5
	v_cmp_lt_i32_e32 vcc, 2, v3
	v_cndmask_b32_e64 v2, v7, v2, s[36:37]
	v_add_u32_e32 v2, s0, v2
	v_cndmask_b32_e32 v7, 0, v6, vcc
	v_add_u32_e32 v38, v7, v3
	v_lshl_add_u32 v55, v2, 2, s8
	v_ashrrev_i32_e32 v39, 31, v38
	v_mad_i64_i32 v[2:3], s[6:7], v55, 9, v[38:39]
	v_lshlrev_b64 v[2:3], 8, v[2:3]
	v_lshlrev_b32_e32 v7, 4, v54
	v_lshl_add_u64 v[2:3], s[20:21], 0, v[2:3]
	v_and_b32_e32 v128, 0xf0, v7
	v_add_u32_e32 v50, 0x300, v122
	v_lshl_add_u64 v[8:9], v[2:3], 0, v[128:129]
	v_mul_hi_i32 v2, v50, s9
	v_lshrrev_b32_e32 v3, 31, v2
	v_ashrrev_i32_e32 v2, 4, v2
	v_add_u32_e32 v2, v2, v3
	v_mul_lo_u32 v3, v2, s12
	v_sub_u32_e32 v56, v50, v3
	v_ashrrev_i32_e32 v3, 4, v56
	v_xad_u32 v7, v2, -1, s5
	v_cmp_lt_i32_e32 vcc, 2, v3
	v_cndmask_b32_e64 v2, v7, v2, s[36:37]
	v_add_u32_e32 v2, s0, v2
	v_cndmask_b32_e32 v7, 0, v6, vcc
	v_add_u32_e32 v40, v7, v3
	v_lshl_add_u32 v57, v2, 2, s8
	v_ashrrev_i32_e32 v41, 31, v40
	v_mad_i64_i32 v[2:3], s[6:7], v57, 9, v[40:41]
	v_lshlrev_b64 v[2:3], 8, v[2:3]
	v_lshlrev_b32_e32 v7, 4, v56
	v_lshl_add_u64 v[2:3], s[20:21], 0, v[2:3]
	v_and_b32_e32 v128, 0xf0, v7
	v_add_u32_e32 v51, 0x400, v122
	v_lshl_add_u64 v[12:13], v[2:3], 0, v[128:129]
	v_mul_hi_i32 v2, v51, s9
	v_lshrrev_b32_e32 v3, 31, v2
	v_ashrrev_i32_e32 v2, 4, v2
	v_add_u32_e32 v2, v2, v3
	v_mul_lo_u32 v3, v2, s12
	v_sub_u32_e32 v7, v51, v3
	v_ashrrev_i32_e32 v3, 4, v7
	v_xad_u32 v10, v2, -1, s5
	v_cmp_lt_i32_e32 vcc, 2, v3
	v_cndmask_b32_e64 v10, v10, v2, s[36:37]
	v_lshlrev_b32_e32 v7, 4, v7
	v_cndmask_b32_e32 v2, 0, v6, vcc
	v_add_u32_e32 v2, v2, v3
	v_add_u32_e32 v3, s0, v10
	v_lshl_add_u32 v10, v3, 2, s8
	v_ashrrev_i32_e32 v3, 31, v2
	v_mad_i64_i32 v[2:3], s[6:7], v10, 9, v[2:3]
	v_lshlrev_b64 v[2:3], 8, v[2:3]
	v_lshl_add_u64 v[2:3], s[20:21], 0, v[2:3]
	v_and_b32_e32 v128, 0xf0, v7
	v_add_u32_e32 v52, 0x500, v122
	v_lshl_add_u64 v[46:47], v[2:3], 0, v[128:129]
	v_mul_hi_i32 v2, v52, s9
	v_lshrrev_b32_e32 v3, 31, v2
	v_ashrrev_i32_e32 v2, 4, v2
	v_add_u32_e32 v2, v2, v3
	v_mul_lo_u32 v3, v2, s12
	v_sub_u32_e32 v18, v52, v3
	v_ashrrev_i32_e32 v3, 4, v18
	v_xad_u32 v7, v2, -1, s5
	v_cmp_lt_i32_e32 vcc, 2, v3
	v_cndmask_b32_e64 v7, v7, v2, s[36:37]
	global_load_dwordx4 v[8:11], v[8:9], off
	v_cndmask_b32_e32 v2, 0, v6, vcc
	v_add_u32_e32 v14, v2, v3
	v_add_u32_e32 v6, s0, v7
	v_lshl_add_u32 v16, v6, 2, s8
	v_ashrrev_i32_e32 v15, 31, v14
	global_load_dwordx4 v[0:3], v[0:1], off
	v_mad_i64_i32 v[14:15], s[6:7], v16, 9, v[14:15]
	global_load_dwordx4 v[4:7], v[4:5], off
	v_lshlrev_b64 v[16:17], 8, v[14:15]
	v_lshlrev_b32_e32 v22, 4, v18
	global_load_dwordx4 v[12:15], v[12:13], off
	v_lshl_add_u64 v[20:21], s[20:21], 0, v[16:17]
	v_and_b32_e32 v128, 0xf0, v22
	global_load_dwordx4 v[16:19], v[46:47], off
	v_lshl_add_u64 v[48:49], v[20:21], 0, v[128:129]
	global_load_dwordx4 v[20:23], v[48:49], off
	s_and_b64 s[6:7], s[36:37], exec
	s_mov_b32 s6, 0xfffdc000
	v_lshlrev_b32_e32 v59, 2, v32
	v_lshlrev_b32_e32 v32, 4, v32
	s_cselect_b32 s7, 0, -1
	s_cselect_b32 s6, 0x24000, s6
	s_cselect_b32 s11, s27, s57
	s_cselect_b32 s14, s26, s56
	s_lshl_b32 s12, s8, 6
	s_ashr_i32 s13, s12, 31
	s_lshl_b64 s[12:13], s[12:13], 2
	s_add_u32 s12, s14, s12
	s_addc_u32 s13, s11, s13
	v_xad_u32 v64, v31, -1, s5
	v_lshlrev_b64 v[34:35], 8, v[34:35]
	s_movk_i32 s5, 0x900
	v_lshlrev_b32_e32 v60, 2, v33
	v_and_b32_e32 v42, 15, v42
	v_lshlrev_b32_e32 v61, 2, v50
	v_lshlrev_b32_e32 v62, 2, v51
	v_lshlrev_b32_e32 v53, 4, v122
	v_lshlrev_b32_e32 v63, 2, v52
	s_mov_b32 s9, 0
	v_lshlrev_b32_e32 v58, 2, v122
	v_lshlrev_b32_e32 v236, 4, v122
	v_cmp_gt_u32_e64 s[48:49], 8, v31
	s_mov_b32 s59, s29
	s_waitcnt vmcnt(4)
	ds_write_b128 v53, v[0:3]
	s_waitcnt vmcnt(3)
	ds_write_b128 v32, v[4:7]
	v_lshlrev_b32_e32 v32, 4, v33
	ds_write_b128 v32, v[8:11]
	v_lshlrev_b32_e32 v32, 4, v50
	s_waitcnt vmcnt(2)
	ds_write_b128 v32, v[12:15]
	v_lshlrev_b32_e32 v32, 4, v51
	s_waitcnt vmcnt(1)
	ds_write_b128 v32, v[16:19]
	v_lshlrev_b32_e32 v32, 4, v52
	s_waitcnt vmcnt(0)
	ds_write_b128 v32, v[20:23]
	v_and_b32_e32 v32, 4, v122
	v_cmp_eq_u32_e64 s[40:41], 0, v32
	v_lshl_add_u64 v[32:33], v[28:29], 2, s[12:13]
	v_mad_i64_i32 v[34:35], s[12:13], v43, s5, v[34:35]
	v_and_b32_e32 v50, 3, v122
	v_lshl_or_b32 v34, v42, 4, v34
	v_cmp_eq_u32_e64 s[38:39], 3, v50
	v_cmp_eq_u32_e64 s[42:43], 0, v50
	v_cmp_eq_u32_e64 s[44:45], 1, v50
	v_cmp_eq_u32_e64 s[46:47], 2, v50
	v_lshl_add_u64 v[50:51], s[20:21], 0, v[34:35]
	v_lshlrev_b64 v[34:35], 8, v[36:37]
	v_mad_i64_i32 v[34:35], s[12:13], v45, s5, v[34:35]
	v_and_b32_e32 v36, 15, v44
	v_lshl_or_b32 v34, v36, 4, v34
	v_lshl_add_u64 v[52:53], s[20:21], 0, v[34:35]
	v_lshlrev_b64 v[34:35], 8, v[38:39]
	v_mad_i64_i32 v[34:35], s[12:13], v55, s5, v[34:35]
	v_and_b32_e32 v36, 15, v54
	v_lshl_or_b32 v34, v36, 4, v34
	v_lshl_add_u64 v[54:55], s[20:21], 0, v[34:35]
	v_lshlrev_b64 v[34:35], 8, v[40:41]
	v_mad_i64_i32 v[34:35], s[12:13], v57, s5, v[34:35]
	v_and_b32_e32 v36, 15, v56
	v_lshl_or_b32 v34, v36, 4, v34
	v_lshl_add_u64 v[56:57], s[20:21], 0, v[34:35]
	v_readfirstlane_b32 s81, v236
	s_waitcnt lgkmcnt(0)
	s_barrier
.LBB0_263:
	s_add_i32 s5, s9, 1
	s_cmp_lt_u32 s5, s1
	s_cselect_b64 s[12:13], -1, 0
	s_cmp_ge_u32 s5, s1
	v_lshl_add_u64 v[34:35], v[50:51], 0, s[6:7]
	v_lshl_add_u64 v[36:37], v[52:53], 0, s[6:7]
	v_lshl_add_u64 v[38:39], v[54:55], 0, s[6:7]
	v_lshl_add_u64 v[40:41], v[56:57], 0, s[6:7]
	v_lshl_add_u64 v[42:43], v[46:47], 0, s[6:7]
	v_lshl_add_u64 v[44:45], v[48:49], 0, s[6:7]
	s_cbranch_scc1 .LBB0_265
	s_bitcmp1_b32 s5, 0
	s_cselect_b32 s80, 0x6000, 0
	s_add_u32 s80, s80, s81
	s_mov_b32 m0, s80
	s_nop 0
	global_load_lds_dwordx4 v[34:35], off
	s_add_u32 m0, s80, 0x1000
	s_nop 0
	global_load_lds_dwordx4 v[36:37], off
	s_add_u32 m0, s80, 0x2000
	s_nop 0
	global_load_lds_dwordx4 v[38:39], off
	s_add_u32 m0, s80, 0x3000
	s_nop 0
	global_load_lds_dwordx4 v[40:41], off
	s_add_u32 m0, s80, 0x4000
	s_nop 0
	global_load_lds_dwordx4 v[42:43], off
	s_add_u32 m0, s80, 0x5000
	s_nop 0
	global_load_lds_dwordx4 v[44:45], off
.LBB0_265:
	s_bitcmp1_b32 s9, 0
	s_cselect_b32 s9, 0x6000, 0
	v_lshl_add_u32 v46, v30, 2, s9
	v_lshl_add_u32 v47, v28, 2, s9
	s_andn2_b64 vcc, exec, s[12:13]
	ds_read_b128 v[72:75], v46 offset:256
	ds_read_b128 v[76:79], v46 offset:768
	ds_read_b128 v[84:87], v46 offset:1280
	ds_read2st64_b32 v[228:229], v47 offset0:2 offset1:8
	ds_read_b128 v[80:83], v46 offset:1024
	ds_read_b128 v[68:71], v46
	ds_read_b128 v[92:95], v46 offset:1792
	ds_read_b128 v[96:99], v46 offset:2304
	ds_read_b128 v[204:207], v46 offset:2816
	ds_read_b128 v[200:203], v46 offset:2560
	ds_read_b128 v[88:91], v46 offset:1536
	s_waitcnt lgkmcnt(5)
	v_pk_mul_f32 v[232:233], v[72:73], v[24:25]
	s_nop 0
	v_pk_fma_f32 v[232:233], v[74:75], v[26:27], v[232:233]
	s_nop 0
	v_add_f32_e32 v232, v232, v233
	ds_read_b128 v[212:215], v46 offset:3328
	ds_read_b128 v[216:219], v46 offset:3840
	ds_read_b128 v[224:227], v46 offset:4352
	ds_read2st64_b32 v[230:231], v47 offset0:14 offset1:20
	ds_read_b128 v[220:223], v46 offset:4096
	ds_read_b128 v[208:211], v46 offset:3072
	v_pk_mul_f32 v[50:51], v[228:229], v[84:85] op_sel_hi:[0,1]
	v_pk_mul_f32 v[52:53], v[228:229], v[86:87] op_sel_hi:[0,1]
	v_add_f32_dpp v232, v232, v232 quad_perm:[1,0,3,2] row_mask:0xf bank_mask:0xf bound_ctrl:1
	v_pk_fma_f32 v[50:51], v[76:77], v[24:25], v[50:51]
	s_nop 0
	v_add_f32_dpp v232, v232, v232 quad_perm:[2,3,0,1] row_mask:0xf bank_mask:0xf bound_ctrl:1
	s_nop 1
	v_add_f32_dpp v232, v232, v232 row_half_mirror row_mask:0xf bank_mask:0xf bound_ctrl:1
	v_pk_fma_f32 v[52:53], v[78:79], v[26:27], v[52:53]
	s_nop 0
	v_add_f32_dpp v232, v232, v232 row_mirror row_mask:0xf bank_mask:0xf bound_ctrl:1
	v_pk_fma_f32 v[24:25], v[80:81], v[232:233], v[50:51] op_sel_hi:[1,0,1] neg_lo:[1,0,0] neg_hi:[1,0,0]
	v_pk_fma_f32 v[26:27], v[82:83], v[232:233], v[52:53] op_sel_hi:[1,0,1] neg_lo:[1,0,0] neg_hi:[1,0,0]
	s_waitcnt lgkmcnt(6)
	v_pk_mul_f32 v[232:233], v[92:93], v[24:25]
	v_pk_mul_f32 v[234:235], v[68:69], v[24:25]
	v_pk_fma_f32 v[232:233], v[94:95], v[26:27], v[232:233]
	v_pk_fma_f32 v[234:235], v[70:71], v[26:27], v[234:235]
	v_add_f32_e32 v232, v232, v233
	v_add_f32_e32 v234, v234, v235
	ds_read_b128 v[72:75], v46 offset:4864
	ds_read_b128 v[76:79], v46 offset:5376
	ds_read_b128 v[84:87], v46 offset:5888
	ds_read_b128 v[80:83], v46 offset:5632
	ds_read_b128 v[68:71], v46 offset:4608
	v_pk_mul_f32 v[50:51], v[228:229], v[204:205] op_sel:[1,0] op_sel_hi:[1,1]
	v_pk_mul_f32 v[52:53], v[228:229], v[206:207] op_sel:[1,0] op_sel_hi:[1,1]
	v_add_f32_dpp v232, v232, v232 quad_perm:[1,0,3,2] row_mask:0xf bank_mask:0xf bound_ctrl:1
	v_add_f32_dpp v234, v234, v234 quad_perm:[1,0,3,2] row_mask:0xf bank_mask:0xf bound_ctrl:1
	v_pk_fma_f32 v[50:51], v[96:97], v[24:25], v[50:51]
	v_add_f32_dpp v232, v232, v232 quad_perm:[2,3,0,1] row_mask:0xf bank_mask:0xf bound_ctrl:1
	v_add_f32_dpp v234, v234, v234 quad_perm:[2,3,0,1] row_mask:0xf bank_mask:0xf bound_ctrl:1
	v_cndmask_b32_e64 v54, 0, v234, s[42:43]
	v_add_f32_dpp v232, v232, v232 row_half_mirror row_mask:0xf bank_mask:0xf bound_ctrl:1
	v_pk_fma_f32 v[52:53], v[98:99], v[26:27], v[52:53]
	s_nop 0
	v_add_f32_dpp v232, v232, v232 row_mirror row_mask:0xf bank_mask:0xf bound_ctrl:1
	v_pk_fma_f32 v[24:25], v[200:201], v[232:233], v[50:51] op_sel_hi:[1,0,1] neg_lo:[1,0,0] neg_hi:[1,0,0]
	v_pk_fma_f32 v[26:27], v[202:203], v[232:233], v[52:53] op_sel_hi:[1,0,1] neg_lo:[1,0,0] neg_hi:[1,0,0]
	s_waitcnt lgkmcnt(5)
	v_pk_mul_f32 v[232:233], v[212:213], v[24:25]
	v_pk_mul_f32 v[234:235], v[88:89], v[24:25]
	v_pk_fma_f32 v[232:233], v[214:215], v[26:27], v[232:233]
	v_pk_fma_f32 v[234:235], v[90:91], v[26:27], v[234:235]
	v_add_f32_e32 v232, v232, v233
	v_add_f32_e32 v234, v234, v235
	ds_read_b128 v[92:95], v46 offset:6400
	ds_read_b128 v[96:99], v46 offset:6912
	ds_read_b128 v[204:207], v46 offset:7424
	ds_read2st64_b32 v[228:229], v47 offset0:26 offset1:32
	ds_read_b128 v[200:203], v46 offset:7168
	ds_read_b128 v[88:91], v46 offset:6144
	v_pk_mul_f32 v[50:51], v[230:231], v[224:225] op_sel_hi:[0,1]
	v_pk_mul_f32 v[52:53], v[230:231], v[226:227] op_sel_hi:[0,1]
	v_add_f32_dpp v232, v232, v232 quad_perm:[1,0,3,2] row_mask:0xf bank_mask:0xf bound_ctrl:1
	v_add_f32_dpp v234, v234, v234 quad_perm:[1,0,3,2] row_mask:0xf bank_mask:0xf bound_ctrl:1
	v_pk_fma_f32 v[50:51], v[216:217], v[24:25], v[50:51]
	v_add_f32_dpp v232, v232, v232 quad_perm:[2,3,0,1] row_mask:0xf bank_mask:0xf bound_ctrl:1
	v_add_f32_dpp v234, v234, v234 quad_perm:[2,3,0,1] row_mask:0xf bank_mask:0xf bound_ctrl:1
	v_cndmask_b32_e64 v54, v54, v234, s[44:45]
	v_add_f32_dpp v232, v232, v232 row_half_mirror row_mask:0xf bank_mask:0xf bound_ctrl:1
	v_pk_fma_f32 v[52:53], v[218:219], v[26:27], v[52:53]
	s_nop 0
	v_add_f32_dpp v232, v232, v232 row_mirror row_mask:0xf bank_mask:0xf bound_ctrl:1
	v_pk_fma_f32 v[24:25], v[220:221], v[232:233], v[50:51] op_sel_hi:[1,0,1] neg_lo:[1,0,0] neg_hi:[1,0,0]
	v_pk_fma_f32 v[26:27], v[222:223], v[232:233], v[52:53] op_sel_hi:[1,0,1] neg_lo:[1,0,0] neg_hi:[1,0,0]
	s_waitcnt lgkmcnt(6)
	v_pk_mul_f32 v[232:233], v[72:73], v[24:25]
	v_pk_mul_f32 v[234:235], v[208:209], v[24:25]
	v_pk_fma_f32 v[232:233], v[74:75], v[26:27], v[232:233]
	v_pk_fma_f32 v[234:235], v[210:211], v[26:27], v[234:235]
	v_add_f32_e32 v232, v232, v233
	v_add_f32_e32 v234, v234, v235
	ds_read_b128 v[212:215], v46 offset:7936
	ds_read_b128 v[216:219], v46 offset:8448
	ds_read_b128 v[224:227], v46 offset:8960
	ds_read_b128 v[220:223], v46 offset:8704
	ds_read_b128 v[208:211], v46 offset:7680
	v_pk_mul_f32 v[50:51], v[230:231], v[84:85] op_sel:[1,0] op_sel_hi:[1,1]
	v_pk_mul_f32 v[52:53], v[230:231], v[86:87] op_sel:[1,0] op_sel_hi:[1,1]
	v_add_f32_dpp v232, v232, v232 quad_perm:[1,0,3,2] row_mask:0xf bank_mask:0xf bound_ctrl:1
	v_add_f32_dpp v234, v234, v234 quad_perm:[1,0,3,2] row_mask:0xf bank_mask:0xf bound_ctrl:1
	v_pk_fma_f32 v[50:51], v[76:77], v[24:25], v[50:51]
	v_add_f32_dpp v232, v232, v232 quad_perm:[2,3,0,1] row_mask:0xf bank_mask:0xf bound_ctrl:1
	v_add_f32_dpp v234, v234, v234 quad_perm:[2,3,0,1] row_mask:0xf bank_mask:0xf bound_ctrl:1
	v_cndmask_b32_e64 v54, v54, v234, s[46:47]
	v_add_f32_dpp v232, v232, v232 row_half_mirror row_mask:0xf bank_mask:0xf bound_ctrl:1
	v_pk_fma_f32 v[52:53], v[78:79], v[26:27], v[52:53]
	s_nop 0
	v_add_f32_dpp v232, v232, v232 row_mirror row_mask:0xf bank_mask:0xf bound_ctrl:1
	v_pk_fma_f32 v[24:25], v[80:81], v[232:233], v[50:51] op_sel_hi:[1,0,1] neg_lo:[1,0,0] neg_hi:[1,0,0]
	v_pk_fma_f32 v[26:27], v[82:83], v[232:233], v[52:53] op_sel_hi:[1,0,1] neg_lo:[1,0,0] neg_hi:[1,0,0]
	s_waitcnt lgkmcnt(5)
	v_pk_mul_f32 v[232:233], v[92:93], v[24:25]
	v_pk_mul_f32 v[234:235], v[68:69], v[24:25]
	v_pk_fma_f32 v[232:233], v[94:95], v[26:27], v[232:233]
	v_pk_fma_f32 v[234:235], v[70:71], v[26:27], v[234:235]
	v_add_f32_e32 v232, v232, v233
	v_add_f32_e32 v234, v234, v235
	ds_read_b128 v[72:75], v46 offset:9472
	ds_read_b128 v[76:79], v46 offset:9984
	ds_read_b128 v[84:87], v46 offset:10496
	ds_read2st64_b32 v[230:231], v47 offset0:38 offset1:44
	ds_read_b128 v[80:83], v46 offset:10240
	ds_read_b128 v[68:71], v46 offset:9216
	v_pk_mul_f32 v[50:51], v[228:229], v[204:205] op_sel_hi:[0,1]
	v_pk_mul_f32 v[52:53], v[228:229], v[206:207] op_sel_hi:[0,1]
	v_add_f32_dpp v232, v232, v232 quad_perm:[1,0,3,2] row_mask:0xf bank_mask:0xf bound_ctrl:1
	v_add_f32_dpp v234, v234, v234 quad_perm:[1,0,3,2] row_mask:0xf bank_mask:0xf bound_ctrl:1
	v_pk_fma_f32 v[50:51], v[96:97], v[24:25], v[50:51]
	v_add_f32_dpp v232, v232, v232 quad_perm:[2,3,0,1] row_mask:0xf bank_mask:0xf bound_ctrl:1
	v_add_f32_dpp v234, v234, v234 quad_perm:[2,3,0,1] row_mask:0xf bank_mask:0xf bound_ctrl:1
	v_cndmask_b32_e64 v54, v54, v234, s[38:39]
	v_add_f32_dpp v232, v232, v232 row_half_mirror row_mask:0xf bank_mask:0xf bound_ctrl:1
	v_pk_fma_f32 v[52:53], v[98:99], v[26:27], v[52:53]
	s_nop 0
	v_add_f32_dpp v232, v232, v232 row_mirror row_mask:0xf bank_mask:0xf bound_ctrl:1
	v_pk_fma_f32 v[24:25], v[200:201], v[232:233], v[50:51] op_sel_hi:[1,0,1] neg_lo:[1,0,0] neg_hi:[1,0,0]
	v_pk_fma_f32 v[26:27], v[202:203], v[232:233], v[52:53] op_sel_hi:[1,0,1] neg_lo:[1,0,0] neg_hi:[1,0,0]
	s_waitcnt lgkmcnt(6)
	v_pk_mul_f32 v[232:233], v[212:213], v[24:25]
	v_pk_mul_f32 v[234:235], v[88:89], v[24:25]
	v_pk_fma_f32 v[232:233], v[214:215], v[26:27], v[232:233]
	v_pk_fma_f32 v[234:235], v[90:91], v[26:27], v[234:235]
	v_add_f32_e32 v232, v232, v233
	v_add_f32_e32 v234, v234, v235
	ds_read_b128 v[92:95], v46 offset:11008
	ds_read_b128 v[96:99], v46 offset:11520
	ds_read_b128 v[204:207], v46 offset:12032
	ds_read_b128 v[200:203], v46 offset:11776
	ds_read_b128 v[88:91], v46 offset:10752
	v_pk_mul_f32 v[50:51], v[228:229], v[224:225] op_sel:[1,0] op_sel_hi:[1,1]
	v_pk_mul_f32 v[52:53], v[228:229], v[226:227] op_sel:[1,0] op_sel_hi:[1,1]
	v_add_f32_dpp v232, v232, v232 quad_perm:[1,0,3,2] row_mask:0xf bank_mask:0xf bound_ctrl:1
	v_add_f32_dpp v234, v234, v234 quad_perm:[1,0,3,2] row_mask:0xf bank_mask:0xf bound_ctrl:1
	v_pk_fma_f32 v[50:51], v[216:217], v[24:25], v[50:51]
	v_add_f32_dpp v232, v232, v232 quad_perm:[2,3,0,1] row_mask:0xf bank_mask:0xf bound_ctrl:1
	v_add_f32_dpp v234, v234, v234 quad_perm:[2,3,0,1] row_mask:0xf bank_mask:0xf bound_ctrl:1
	v_cndmask_b32_e64 v55, 0, v234, s[42:43]
	v_add_f32_dpp v232, v232, v232 row_half_mirror row_mask:0xf bank_mask:0xf bound_ctrl:1
	v_pk_fma_f32 v[52:53], v[218:219], v[26:27], v[52:53]
	s_nop 0
	v_add_f32_dpp v232, v232, v232 row_mirror row_mask:0xf bank_mask:0xf bound_ctrl:1
	v_pk_fma_f32 v[24:25], v[220:221], v[232:233], v[50:51] op_sel_hi:[1,0,1] neg_lo:[1,0,0] neg_hi:[1,0,0]
	v_pk_fma_f32 v[26:27], v[222:223], v[232:233], v[52:53] op_sel_hi:[1,0,1] neg_lo:[1,0,0] neg_hi:[1,0,0]
	s_waitcnt lgkmcnt(5)
	v_pk_mul_f32 v[232:233], v[72:73], v[24:25]
	v_pk_mul_f32 v[234:235], v[208:209], v[24:25]
	v_pk_fma_f32 v[232:233], v[74:75], v[26:27], v[232:233]
	v_pk_fma_f32 v[234:235], v[210:211], v[26:27], v[234:235]
	v_add_f32_e32 v232, v232, v233
	v_add_f32_e32 v234, v234, v235
	ds_read_b128 v[212:215], v46 offset:12544
	ds_read_b128 v[216:219], v46 offset:13056
	ds_read_b128 v[224:227], v46 offset:13568
	ds_read2st64_b32 v[228:229], v47 offset0:50 offset1:56
	ds_read_b128 v[220:223], v46 offset:13312
	ds_read_b128 v[208:211], v46 offset:12288
	v_pk_mul_f32 v[50:51], v[230:231], v[84:85] op_sel_hi:[0,1]
	v_pk_mul_f32 v[52:53], v[230:231], v[86:87] op_sel_hi:[0,1]
	v_add_f32_dpp v232, v232, v232 quad_perm:[1,0,3,2] row_mask:0xf bank_mask:0xf bound_ctrl:1
	v_add_f32_dpp v234, v234, v234 quad_perm:[1,0,3,2] row_mask:0xf bank_mask:0xf bound_ctrl:1
	v_pk_fma_f32 v[50:51], v[76:77], v[24:25], v[50:51]
	v_add_f32_dpp v232, v232, v232 quad_perm:[2,3,0,1] row_mask:0xf bank_mask:0xf bound_ctrl:1
	v_add_f32_dpp v234, v234, v234 quad_perm:[2,3,0,1] row_mask:0xf bank_mask:0xf bound_ctrl:1
	v_cndmask_b32_e64 v55, v55, v234, s[44:45]
	v_add_f32_dpp v232, v232, v232 row_half_mirror row_mask:0xf bank_mask:0xf bound_ctrl:1
	v_pk_fma_f32 v[52:53], v[78:79], v[26:27], v[52:53]
	s_nop 0
	v_add_f32_dpp v232, v232, v232 row_mirror row_mask:0xf bank_mask:0xf bound_ctrl:1
	v_pk_fma_f32 v[24:25], v[80:81], v[232:233], v[50:51] op_sel_hi:[1,0,1] neg_lo:[1,0,0] neg_hi:[1,0,0]
	v_pk_fma_f32 v[26:27], v[82:83], v[232:233], v[52:53] op_sel_hi:[1,0,1] neg_lo:[1,0,0] neg_hi:[1,0,0]
	s_waitcnt lgkmcnt(6)
	v_pk_mul_f32 v[232:233], v[92:93], v[24:25]
	v_pk_mul_f32 v[234:235], v[68:69], v[24:25]
	v_pk_fma_f32 v[232:233], v[94:95], v[26:27], v[232:233]
	v_pk_fma_f32 v[234:235], v[70:71], v[26:27], v[234:235]
	v_add_f32_e32 v232, v232, v233
	v_add_f32_e32 v234, v234, v235
	ds_read_b128 v[72:75], v46 offset:14080
	ds_read_b128 v[76:79], v46 offset:14592
	ds_read_b128 v[84:87], v46 offset:15104
	ds_read_b128 v[80:83], v46 offset:14848
	ds_read_b128 v[68:71], v46 offset:13824
	v_pk_mul_f32 v[50:51], v[230:231], v[204:205] op_sel:[1,0] op_sel_hi:[1,1]
	v_pk_mul_f32 v[52:53], v[230:231], v[206:207] op_sel:[1,0] op_sel_hi:[1,1]
	v_add_f32_dpp v232, v232, v232 quad_perm:[1,0,3,2] row_mask:0xf bank_mask:0xf bound_ctrl:1
	v_add_f32_dpp v234, v234, v234 quad_perm:[1,0,3,2] row_mask:0xf bank_mask:0xf bound_ctrl:1
	v_pk_fma_f32 v[50:51], v[96:97], v[24:25], v[50:51]
	v_add_f32_dpp v232, v232, v232 quad_perm:[2,3,0,1] row_mask:0xf bank_mask:0xf bound_ctrl:1
	v_add_f32_dpp v234, v234, v234 quad_perm:[2,3,0,1] row_mask:0xf bank_mask:0xf bound_ctrl:1
	v_cndmask_b32_e64 v55, v55, v234, s[46:47]
	v_add_f32_dpp v232, v232, v232 row_half_mirror row_mask:0xf bank_mask:0xf bound_ctrl:1
	v_pk_fma_f32 v[52:53], v[98:99], v[26:27], v[52:53]
	s_nop 0
	v_add_f32_dpp v232, v232, v232 row_mirror row_mask:0xf bank_mask:0xf bound_ctrl:1
	v_pk_fma_f32 v[24:25], v[200:201], v[232:233], v[50:51] op_sel_hi:[1,0,1] neg_lo:[1,0,0] neg_hi:[1,0,0]
	v_pk_fma_f32 v[26:27], v[202:203], v[232:233], v[52:53] op_sel_hi:[1,0,1] neg_lo:[1,0,0] neg_hi:[1,0,0]
	s_waitcnt lgkmcnt(5)
	v_pk_mul_f32 v[232:233], v[212:213], v[24:25]
	v_pk_mul_f32 v[234:235], v[88:89], v[24:25]
	v_pk_fma_f32 v[232:233], v[214:215], v[26:27], v[232:233]
	v_pk_fma_f32 v[234:235], v[90:91], v[26:27], v[234:235]
	v_add_f32_e32 v232, v232, v233
	v_add_f32_e32 v234, v234, v235
	ds_read_b128 v[92:95], v46 offset:15616
	ds_read_b128 v[96:99], v46 offset:16128
	ds_read_b128 v[204:207], v46 offset:16640
	ds_read2st64_b32 v[230:231], v47 offset0:62 offset1:68
	ds_read_b128 v[200:203], v46 offset:16384
	ds_read_b128 v[88:91], v46 offset:15360
	v_pk_mul_f32 v[50:51], v[228:229], v[224:225] op_sel_hi:[0,1]
	v_pk_mul_f32 v[52:53], v[228:229], v[226:227] op_sel_hi:[0,1]
	v_add_f32_dpp v232, v232, v232 quad_perm:[1,0,3,2] row_mask:0xf bank_mask:0xf bound_ctrl:1
	v_add_f32_dpp v234, v234, v234 quad_perm:[1,0,3,2] row_mask:0xf bank_mask:0xf bound_ctrl:1
	v_pk_fma_f32 v[50:51], v[216:217], v[24:25], v[50:51]
	v_add_f32_dpp v232, v232, v232 quad_perm:[2,3,0,1] row_mask:0xf bank_mask:0xf bound_ctrl:1
	v_add_f32_dpp v234, v234, v234 quad_perm:[2,3,0,1] row_mask:0xf bank_mask:0xf bound_ctrl:1
	v_cndmask_b32_e64 v55, v55, v234, s[38:39]
	v_add_f32_dpp v232, v232, v232 row_half_mirror row_mask:0xf bank_mask:0xf bound_ctrl:1
	v_pk_fma_f32 v[52:53], v[218:219], v[26:27], v[52:53]
	s_nop 0
	v_add_f32_dpp v232, v232, v232 row_mirror row_mask:0xf bank_mask:0xf bound_ctrl:1
	v_pk_fma_f32 v[24:25], v[220:221], v[232:233], v[50:51] op_sel_hi:[1,0,1] neg_lo:[1,0,0] neg_hi:[1,0,0]
	v_pk_fma_f32 v[26:27], v[222:223], v[232:233], v[52:53] op_sel_hi:[1,0,1] neg_lo:[1,0,0] neg_hi:[1,0,0]
	s_waitcnt lgkmcnt(6)
	v_pk_mul_f32 v[232:233], v[72:73], v[24:25]
	v_pk_mul_f32 v[234:235], v[208:209], v[24:25]
	v_pk_fma_f32 v[232:233], v[74:75], v[26:27], v[232:233]
	v_pk_fma_f32 v[234:235], v[210:211], v[26:27], v[234:235]
	v_add_f32_e32 v232, v232, v233
	v_add_f32_e32 v234, v234, v235
	ds_read_b128 v[212:215], v46 offset:17152
	ds_read_b128 v[216:219], v46 offset:17664
	ds_read_b128 v[224:227], v46 offset:18176
	ds_read_b128 v[220:223], v46 offset:17920
	ds_read_b128 v[208:211], v46 offset:16896
	v_pk_mul_f32 v[50:51], v[228:229], v[84:85] op_sel:[1,0] op_sel_hi:[1,1]
	v_pk_mul_f32 v[52:53], v[228:229], v[86:87] op_sel:[1,0] op_sel_hi:[1,1]
	v_add_f32_dpp v232, v232, v232 quad_perm:[1,0,3,2] row_mask:0xf bank_mask:0xf bound_ctrl:1
	v_add_f32_dpp v234, v234, v234 quad_perm:[1,0,3,2] row_mask:0xf bank_mask:0xf bound_ctrl:1
	v_pk_fma_f32 v[50:51], v[76:77], v[24:25], v[50:51]
	v_add_f32_dpp v232, v232, v232 quad_perm:[2,3,0,1] row_mask:0xf bank_mask:0xf bound_ctrl:1
	v_add_f32_dpp v234, v234, v234 quad_perm:[2,3,0,1] row_mask:0xf bank_mask:0xf bound_ctrl:1
	v_cndmask_b32_e64 v56, 0, v234, s[42:43]
	v_add_f32_dpp v232, v232, v232 row_half_mirror row_mask:0xf bank_mask:0xf bound_ctrl:1
	v_pk_fma_f32 v[52:53], v[78:79], v[26:27], v[52:53]
	v_add_f32_dpp v54, v54, v54 row_ror:8 row_mask:0xf bank_mask:0xf bound_ctrl:1
	v_add_f32_dpp v55, v55, v55 row_ror:8 row_mask:0xf bank_mask:0xf bound_ctrl:1
	v_add_f32_dpp v232, v232, v232 row_mirror row_mask:0xf bank_mask:0xf bound_ctrl:1
	v_pk_fma_f32 v[24:25], v[80:81], v[232:233], v[50:51] op_sel_hi:[1,0,1] neg_lo:[1,0,0] neg_hi:[1,0,0]
	v_pk_fma_f32 v[26:27], v[82:83], v[232:233], v[52:53] op_sel_hi:[1,0,1] neg_lo:[1,0,0] neg_hi:[1,0,0]
	s_waitcnt lgkmcnt(5)
	v_pk_mul_f32 v[232:233], v[92:93], v[24:25]
	v_pk_mul_f32 v[234:235], v[68:69], v[24:25]
	v_pk_fma_f32 v[232:233], v[94:95], v[26:27], v[232:233]
	v_pk_fma_f32 v[234:235], v[70:71], v[26:27], v[234:235]
	v_add_f32_e32 v232, v232, v233
	v_add_f32_e32 v234, v234, v235
	ds_read_b128 v[72:75], v46 offset:18688
	ds_read_b128 v[76:79], v46 offset:19200
	ds_read_b128 v[84:87], v46 offset:19712
	ds_read2st64_b32 v[228:229], v47 offset0:74 offset1:80
	ds_read_b128 v[80:83], v46 offset:19456
	ds_read_b128 v[68:71], v46 offset:18432
	v_pk_mul_f32 v[50:51], v[230:231], v[204:205] op_sel_hi:[0,1]
	v_pk_mul_f32 v[52:53], v[230:231], v[206:207] op_sel_hi:[0,1]
	v_add_f32_dpp v232, v232, v232 quad_perm:[1,0,3,2] row_mask:0xf bank_mask:0xf bound_ctrl:1
	v_add_f32_dpp v234, v234, v234 quad_perm:[1,0,3,2] row_mask:0xf bank_mask:0xf bound_ctrl:1
	v_pk_fma_f32 v[50:51], v[96:97], v[24:25], v[50:51]
	v_add_f32_dpp v232, v232, v232 quad_perm:[2,3,0,1] row_mask:0xf bank_mask:0xf bound_ctrl:1
	v_add_f32_dpp v234, v234, v234 quad_perm:[2,3,0,1] row_mask:0xf bank_mask:0xf bound_ctrl:1
	v_cndmask_b32_e64 v56, v56, v234, s[44:45]
	v_add_f32_dpp v232, v232, v232 row_half_mirror row_mask:0xf bank_mask:0xf bound_ctrl:1
	v_pk_fma_f32 v[52:53], v[98:99], v[26:27], v[52:53]
	v_add_f32_dpp v54, v54, v54 row_ror:4 row_mask:0xf bank_mask:0xf bound_ctrl:1
	v_add_f32_dpp v55, v55, v55 row_ror:4 row_mask:0xf bank_mask:0xf bound_ctrl:1
	v_add_f32_dpp v232, v232, v232 row_mirror row_mask:0xf bank_mask:0xf bound_ctrl:1
	v_pk_fma_f32 v[24:25], v[200:201], v[232:233], v[50:51] op_sel_hi:[1,0,1] neg_lo:[1,0,0] neg_hi:[1,0,0]
	v_pk_fma_f32 v[26:27], v[202:203], v[232:233], v[52:53] op_sel_hi:[1,0,1] neg_lo:[1,0,0] neg_hi:[1,0,0]
	s_waitcnt lgkmcnt(6)
	v_pk_mul_f32 v[232:233], v[212:213], v[24:25]
	v_pk_mul_f32 v[234:235], v[88:89], v[24:25]
	v_pk_fma_f32 v[232:233], v[214:215], v[26:27], v[232:233]
	v_pk_fma_f32 v[234:235], v[90:91], v[26:27], v[234:235]
	v_add_f32_e32 v232, v232, v233
	v_add_f32_e32 v234, v234, v235
	ds_read_b128 v[92:95], v46 offset:20224
	ds_read_b128 v[96:99], v46 offset:20736
	ds_read_b128 v[204:207], v46 offset:21248
	ds_read_b128 v[200:203], v46 offset:20992
	ds_read_b128 v[88:91], v46 offset:19968
	v_pk_mul_f32 v[50:51], v[230:231], v[224:225] op_sel:[1,0] op_sel_hi:[1,1]
	v_pk_mul_f32 v[52:53], v[230:231], v[226:227] op_sel:[1,0] op_sel_hi:[1,1]
	v_add_f32_dpp v232, v232, v232 quad_perm:[1,0,3,2] row_mask:0xf bank_mask:0xf bound_ctrl:1
	v_add_f32_dpp v234, v234, v234 quad_perm:[1,0,3,2] row_mask:0xf bank_mask:0xf bound_ctrl:1
	v_pk_fma_f32 v[50:51], v[216:217], v[24:25], v[50:51]
	v_add_f32_dpp v232, v232, v232 quad_perm:[2,3,0,1] row_mask:0xf bank_mask:0xf bound_ctrl:1
	v_add_f32_dpp v234, v234, v234 quad_perm:[2,3,0,1] row_mask:0xf bank_mask:0xf bound_ctrl:1
	v_cndmask_b32_e64 v56, v56, v234, s[46:47]
	v_add_f32_dpp v232, v232, v232 row_half_mirror row_mask:0xf bank_mask:0xf bound_ctrl:1
	v_pk_fma_f32 v[52:53], v[218:219], v[26:27], v[52:53]
	v_cndmask_b32_e64 v49, v55, v54, s[40:41]
	v_cndmask_b32_e64 v48, 0, v49, s[48:49]
	v_add_f32_dpp v232, v232, v232 row_mirror row_mask:0xf bank_mask:0xf bound_ctrl:1
	v_pk_fma_f32 v[24:25], v[220:221], v[232:233], v[50:51] op_sel_hi:[1,0,1] neg_lo:[1,0,0] neg_hi:[1,0,0]
	v_pk_fma_f32 v[26:27], v[222:223], v[232:233], v[52:53] op_sel_hi:[1,0,1] neg_lo:[1,0,0] neg_hi:[1,0,0]
	s_waitcnt lgkmcnt(5)
	v_pk_mul_f32 v[232:233], v[72:73], v[24:25]
	v_pk_mul_f32 v[234:235], v[208:209], v[24:25]
	v_pk_fma_f32 v[232:233], v[74:75], v[26:27], v[232:233]
	v_pk_fma_f32 v[234:235], v[210:211], v[26:27], v[234:235]
	v_add_f32_e32 v232, v232, v233
	v_add_f32_e32 v234, v234, v235
	ds_read_b128 v[212:215], v46 offset:21760
	ds_read_b128 v[216:219], v46 offset:22272
	ds_read_b128 v[224:227], v46 offset:22784
	ds_read2st64_b32 v[230:231], v47 offset0:86 offset1:92
	ds_read_b128 v[220:223], v46 offset:22528
	ds_read_b128 v[208:211], v46 offset:21504
	v_pk_mul_f32 v[50:51], v[228:229], v[84:85] op_sel_hi:[0,1]
	v_pk_mul_f32 v[52:53], v[228:229], v[86:87] op_sel_hi:[0,1]
	v_add_f32_dpp v232, v232, v232 quad_perm:[1,0,3,2] row_mask:0xf bank_mask:0xf bound_ctrl:1
	v_add_f32_dpp v234, v234, v234 quad_perm:[1,0,3,2] row_mask:0xf bank_mask:0xf bound_ctrl:1
	v_pk_fma_f32 v[50:51], v[76:77], v[24:25], v[50:51]
	v_add_f32_dpp v232, v232, v232 quad_perm:[2,3,0,1] row_mask:0xf bank_mask:0xf bound_ctrl:1
	v_add_f32_dpp v234, v234, v234 quad_perm:[2,3,0,1] row_mask:0xf bank_mask:0xf bound_ctrl:1
	v_cndmask_b32_e64 v56, v56, v234, s[38:39]
	v_add_f32_dpp v232, v232, v232 row_half_mirror row_mask:0xf bank_mask:0xf bound_ctrl:1
	v_pk_fma_f32 v[52:53], v[78:79], v[26:27], v[52:53]
	s_nop 0
	v_add_f32_dpp v232, v232, v232 row_mirror row_mask:0xf bank_mask:0xf bound_ctrl:1
	v_pk_fma_f32 v[24:25], v[80:81], v[232:233], v[50:51] op_sel_hi:[1,0,1] neg_lo:[1,0,0] neg_hi:[1,0,0]
	v_pk_fma_f32 v[26:27], v[82:83], v[232:233], v[52:53] op_sel_hi:[1,0,1] neg_lo:[1,0,0] neg_hi:[1,0,0]
	s_waitcnt lgkmcnt(6)
	v_pk_mul_f32 v[232:233], v[92:93], v[24:25]
	v_pk_mul_f32 v[234:235], v[68:69], v[24:25]
	v_pk_fma_f32 v[232:233], v[94:95], v[26:27], v[232:233]
	v_pk_fma_f32 v[234:235], v[70:71], v[26:27], v[234:235]
	v_add_f32_e32 v232, v232, v233
	v_add_f32_e32 v234, v234, v235
	ds_read_b128 v[72:75], v46 offset:23296
	ds_read_b128 v[76:79], v46 offset:23808
	ds_read_b128 v[84:87], v46 offset:24320
	ds_read_b128 v[80:83], v46 offset:24064
	ds_read_b128 v[68:71], v46 offset:23040
	v_pk_mul_f32 v[50:51], v[228:229], v[204:205] op_sel:[1,0] op_sel_hi:[1,1]
	v_pk_mul_f32 v[52:53], v[228:229], v[206:207] op_sel:[1,0] op_sel_hi:[1,1]
	v_add_f32_dpp v232, v232, v232 quad_perm:[1,0,3,2] row_mask:0xf bank_mask:0xf bound_ctrl:1
	v_add_f32_dpp v234, v234, v234 quad_perm:[1,0,3,2] row_mask:0xf bank_mask:0xf bound_ctrl:1
	v_pk_fma_f32 v[50:51], v[96:97], v[24:25], v[50:51]
	v_add_f32_dpp v232, v232, v232 quad_perm:[2,3,0,1] row_mask:0xf bank_mask:0xf bound_ctrl:1
	v_add_f32_dpp v234, v234, v234 quad_perm:[2,3,0,1] row_mask:0xf bank_mask:0xf bound_ctrl:1
	v_cndmask_b32_e64 v57, 0, v234, s[42:43]
	v_add_f32_dpp v232, v232, v232 row_half_mirror row_mask:0xf bank_mask:0xf bound_ctrl:1
	v_pk_fma_f32 v[52:53], v[98:99], v[26:27], v[52:53]
	s_nop 0
	v_add_f32_dpp v232, v232, v232 row_mirror row_mask:0xf bank_mask:0xf bound_ctrl:1
	v_pk_fma_f32 v[24:25], v[200:201], v[232:233], v[50:51] op_sel_hi:[1,0,1] neg_lo:[1,0,0] neg_hi:[1,0,0]
	v_pk_fma_f32 v[26:27], v[202:203], v[232:233], v[52:53] op_sel_hi:[1,0,1] neg_lo:[1,0,0] neg_hi:[1,0,0]
	s_waitcnt lgkmcnt(5)
	v_pk_mul_f32 v[232:233], v[212:213], v[24:25]
	v_pk_mul_f32 v[234:235], v[88:89], v[24:25]
	v_pk_fma_f32 v[232:233], v[214:215], v[26:27], v[232:233]
	v_pk_fma_f32 v[234:235], v[90:91], v[26:27], v[234:235]
	v_add_f32_e32 v232, v232, v233
	v_add_f32_e32 v234, v234, v235
	v_pk_mul_f32 v[50:51], v[230:231], v[224:225] op_sel_hi:[0,1]
	v_pk_mul_f32 v[52:53], v[230:231], v[226:227] op_sel_hi:[0,1]
	v_add_f32_dpp v232, v232, v232 quad_perm:[1,0,3,2] row_mask:0xf bank_mask:0xf bound_ctrl:1
	v_add_f32_dpp v234, v234, v234 quad_perm:[1,0,3,2] row_mask:0xf bank_mask:0xf bound_ctrl:1
	v_pk_fma_f32 v[50:51], v[216:217], v[24:25], v[50:51]
	v_add_f32_dpp v232, v232, v232 quad_perm:[2,3,0,1] row_mask:0xf bank_mask:0xf bound_ctrl:1
	v_add_f32_dpp v234, v234, v234 quad_perm:[2,3,0,1] row_mask:0xf bank_mask:0xf bound_ctrl:1
	v_cndmask_b32_e64 v57, v57, v234, s[44:45]
	v_add_f32_dpp v232, v232, v232 row_half_mirror row_mask:0xf bank_mask:0xf bound_ctrl:1
	v_pk_fma_f32 v[52:53], v[218:219], v[26:27], v[52:53]
	s_nop 0
	v_add_f32_dpp v232, v232, v232 row_mirror row_mask:0xf bank_mask:0xf bound_ctrl:1
	v_pk_fma_f32 v[24:25], v[220:221], v[232:233], v[50:51] op_sel_hi:[1,0,1] neg_lo:[1,0,0] neg_hi:[1,0,0]
	v_pk_fma_f32 v[26:27], v[222:223], v[232:233], v[52:53] op_sel_hi:[1,0,1] neg_lo:[1,0,0] neg_hi:[1,0,0]
	s_waitcnt lgkmcnt(0)
	v_pk_mul_f32 v[232:233], v[72:73], v[24:25]
	v_pk_mul_f32 v[234:235], v[208:209], v[24:25]
	v_pk_fma_f32 v[232:233], v[74:75], v[26:27], v[232:233]
	v_pk_fma_f32 v[234:235], v[210:211], v[26:27], v[234:235]
	v_add_f32_e32 v232, v232, v233
	v_add_f32_e32 v234, v234, v235
	v_pk_mul_f32 v[50:51], v[230:231], v[84:85] op_sel:[1,0] op_sel_hi:[1,1]
	v_pk_mul_f32 v[52:53], v[230:231], v[86:87] op_sel:[1,0] op_sel_hi:[1,1]
	v_add_f32_dpp v232, v232, v232 quad_perm:[1,0,3,2] row_mask:0xf bank_mask:0xf bound_ctrl:1
	v_add_f32_dpp v234, v234, v234 quad_perm:[1,0,3,2] row_mask:0xf bank_mask:0xf bound_ctrl:1
	v_pk_fma_f32 v[50:51], v[76:77], v[24:25], v[50:51]
	v_add_f32_dpp v232, v232, v232 quad_perm:[2,3,0,1] row_mask:0xf bank_mask:0xf bound_ctrl:1
	v_add_f32_dpp v234, v234, v234 quad_perm:[2,3,0,1] row_mask:0xf bank_mask:0xf bound_ctrl:1
	v_cndmask_b32_e64 v57, v57, v234, s[46:47]
	v_add_f32_dpp v232, v232, v232 row_half_mirror row_mask:0xf bank_mask:0xf bound_ctrl:1
	v_pk_fma_f32 v[52:53], v[78:79], v[26:27], v[52:53]
	s_nop 0
	v_add_f32_dpp v232, v232, v232 row_mirror row_mask:0xf bank_mask:0xf bound_ctrl:1
	v_pk_fma_f32 v[24:25], v[80:81], v[232:233], v[50:51] op_sel_hi:[1,0,1] neg_lo:[1,0,0] neg_hi:[1,0,0]
	v_pk_fma_f32 v[26:27], v[82:83], v[232:233], v[52:53] op_sel_hi:[1,0,1] neg_lo:[1,0,0] neg_hi:[1,0,0]
	v_pk_mul_f32 v[234:235], v[68:69], v[24:25]
	s_nop 0
	v_pk_fma_f32 v[234:235], v[70:71], v[26:27], v[234:235]
	s_nop 0
	v_add_f32_e32 v234, v234, v235
	s_nop 1
	v_add_f32_dpp v234, v234, v234 quad_perm:[1,0,3,2] row_mask:0xf bank_mask:0xf bound_ctrl:1
	s_nop 1
	v_add_f32_dpp v234, v234, v234 quad_perm:[2,3,0,1] row_mask:0xf bank_mask:0xf bound_ctrl:1
	v_cndmask_b32_e64 v57, v57, v234, s[38:39]
	v_add_f32_dpp v56, v56, v56 row_ror:8 row_mask:0xf bank_mask:0xf bound_ctrl:1
	s_nop 0
	v_add_f32_dpp v57, v57, v57 row_ror:8 row_mask:0xf bank_mask:0xf bound_ctrl:1
	v_add_f32_dpp v56, v56, v56 row_ror:4 row_mask:0xf bank_mask:0xf bound_ctrl:1
	s_nop 0
	v_add_f32_dpp v57, v57, v57 row_ror:4 row_mask:0xf bank_mask:0xf bound_ctrl:1
	v_cndmask_b32_e64 v49, v57, v56, s[40:41]
	v_cndmask_b32_e64 v48, v49, v48, s[48:49]
	v_cndmask_b32_e64 v46, v64, v31, s[36:37]
	v_add_u32_e32 v46, s0, v46
	v_ashrrev_i32_e32 v47, 31, v46
	v_lshlrev_b64 v[46:47], 10, v[46:47]
	v_lshl_add_u64 v[46:47], v[32:33], 0, v[46:47]
	s_waitcnt vmcnt(0)
	global_store_dword v[46:47], v48, off
	s_waitcnt lgkmcnt(0)
	v_add_u32_e32 v31, 16, v31
	s_cmp_eq_u32 s1, s5
	v_add_u32_e32 v64, -16, v64
	s_barrier
	s_cbranch_scc1 .LBB0_269
	v_mov_b64_e32 v[48:49], v[44:45]
	v_mov_b64_e32 v[46:47], v[42:43]
	v_mov_b64_e32 v[56:57], v[40:41]
	v_mov_b64_e32 v[54:55], v[38:39]
	v_mov_b64_e32 v[52:53], v[36:37]
	v_mov_b64_e32 v[50:51], v[34:35]
	s_mov_b32 s9, s5
	s_branch .LBB0_263
